# conv_phase inner loop: 8 per-iteration loads renamed to fresh VGPRs and software-prefetched one iteration ahead (rolling), counted vmcnt waits
# speedup vs baseline: 1.0088x; 1.0064x over previous
; DI unsigned pk2(float a, float b) { f32x2 v = {a, b}; bf16x2_t r = __builtin_convertvector(v, bf16x2_t); return __builtin_bit_cast(unsigned, r); }
; DI float gelu_tanh(float x) { const float u = 0.7978845608028654f * (x + 0.044715f * x * x * x); return x * __builtin_amdgcn_rcpf(1.f + __builtin_amdgcn_exp2f(-2.f * 1.4426950408889634f * u)); }
; DI f32x8_ unpk8(u32x4 a) { return (f32x8_){bflo(a.x), bfhi(a.x), bflo(a.y), bfhi(a.y), bflo(a.z), bfhi(a.z), bflo(a.w), bfhi(a.w)}; }
; DI void conv_phase(const bf16_t* UP, bf16_t* ACT, const float* cw, const float* cb, int gtid, int nthr) {
;     constexpr int NG = DFF / 8, RUN = 16, NTASK = (MC / RUN) * NG;
;     for (int task = gtid; task < NTASK; task += nthr) {
;         const int cgp = task % NG, tr = task / NG, c0 = cgp * 8, r0 = tr * RUN, tpos = r0 % SEQ;
;         f32x8_ wg[3], wv[3];
; #pragma unroll
;         for (int j = 0; j < 3; ++j) { wg[j] = ld8(cw + (size_t)j * NUP + c0); wv[j] = ld8(cw + (size_t)j * NUP + DFF + c0); }
;         const f32x8_ bg = ld8(cb + c0), bv = ld8(cb + DFF + c0);
;         f32x8_ g2 = {0.f, 0.f, 0.f, 0.f, 0.f, 0.f, 0.f, 0.f}, g1 = g2, v2 = g2, v1 = g2;
;         const bf16_t* up = UP + (size_t)r0 * NUP + c0;
;         if (tpos != 0) {
;             g2 = unpk8(*(const u32x4*)(up - 2 * (size_t)NUP)); g1 = unpk8(*(const u32x4*)(up - (size_t)NUP));
;             v2 = unpk8(*(const u32x4*)(up - 2 * (size_t)NUP + DFF)); v1 = unpk8(*(const u32x4*)(up - (size_t)NUP + DFF));
;         }
; #pragma unroll 4
;         for (int i = 0; i < RUN; ++i) {
;             const f32x8_ g0 = unpk8(__builtin_nontemporal_load((const u32x4*)(up + (size_t)i * NUP))), v0 = unpk8(__builtin_nontemporal_load((const u32x4*)(up + (size_t)i * NUP + DFF)));
;             const f32x8_ cg_ = bg + wg[0] * g2 + wg[1] * g1 + wg[2] * g0, cv = bv + wv[0] * v2 + wv[1] * v1 + wv[2] * v0;
;             u32x4 o; o.x = pk2(gelu_tanh(cg_[0]) * cv[0], gelu_tanh(cg_[1]) * cv[1]); o.y = pk2(gelu_tanh(cg_[2]) * cv[2], gelu_tanh(cg_[3]) * cv[3]);
;             o.z = pk2(gelu_tanh(cg_[4]) * cv[4], gelu_tanh(cg_[5]) * cv[5]); o.w = pk2(gelu_tanh(cg_[6]) * cv[6], gelu_tanh(cg_[7]) * cv[7]);
;             __builtin_nontemporal_store(o, (u32x4*)(ACT + (size_t)(r0 + i) * DFF + c0));
;             g2 = g1; g1 = g0; v2 = v1; v1 = v0;
;         }
.LBB0_912:
	s_or_b64 exec, exec, s[38:39]
	v_mov_b64_e32 v[100:101], s[34:35]
	s_movk_i32 s38, 0x1600
	v_mad_i64_i32 v[100:101], s[38:39], v108, s38, v[100:101]
	v_lshlrev_b64 v[96:97], 1, v[96:97]
	v_lshl_add_u64 v[102:103], s[12:13], 0, v[106:107]
	s_mov_b32 s38, 16
	s_waitcnt vmcnt(0)
	v_lshl_add_u64 v[176:177], v[102:103], 0, v[96:97]
	s_mov_b64 s[40:41], 0x9200000
	v_lshl_add_u64 v[176:177], v[176:177], 0, s[40:41]
	s_mov_b64 s[46:47], 0x2000
	global_load_dwordx4 v[144:147], v[176:177], off nt
	v_lshl_add_u64 v[176:177], v[176:177], 0, s[46:47]
	global_load_dwordx4 v[148:151], v[176:177], off offset:-2560 nt
	global_load_dwordx4 v[152:155], v[176:177], off offset:3072 nt
	v_lshl_add_u64 v[176:177], v[176:177], 0, s[46:47]
	global_load_dwordx4 v[156:159], v[176:177], off offset:512 nt
	v_lshl_add_u64 v[176:177], v[176:177], 0, s[46:47]
	global_load_dwordx4 v[160:163], v[176:177], off offset:-2048 nt
	global_load_dwordx4 v[164:167], v[176:177], off offset:3584 nt
	v_lshl_add_u64 v[176:177], v[176:177], 0, s[46:47]
	global_load_dwordx4 v[168:171], v[176:177], off offset:1024 nt
	v_lshl_add_u64 v[176:177], v[176:177], 0, s[46:47]
	global_load_dwordx4 v[172:175], v[176:177], off offset:-1536 nt
.LBB0_913:
	s_nop 0
	v_lshl_add_u64 v[104:105], v[102:103], 0, v[96:97]
	s_mov_b64 s[40:41], 0x920b000
	v_lshl_add_u64 v[176:177], v[104:105], 0, s[40:41]
	s_mov_b32 s39, 0x9201000
	s_nop 0
	v_pk_fma_f32 v[24:25], v[36:37], v[24:25], v[84:85]
	v_pk_fma_f32 v[24:25], v[52:53], v[8:9], v[24:25]
	v_pk_fma_f32 v[16:17], v[44:45], v[16:17], v[92:93]
	v_pk_fma_f32 v[26:27], v[38:39], v[26:27], v[86:87]
	v_pk_fma_f32 v[16:17], v[60:61], v[0:1], v[16:17]
	v_pk_fma_f32 v[26:27], v[54:55], v[10:11], v[26:27]
	v_pk_fma_f32 v[18:19], v[46:47], v[18:19], v[94:95]
	v_pk_fma_f32 v[28:29], v[32:33], v[28:29], v[80:81]
	v_pk_fma_f32 v[18:19], v[62:63], v[2:3], v[18:19]
	v_pk_fma_f32 v[28:29], v[48:49], v[12:13], v[28:29]
	v_pk_fma_f32 v[20:21], v[40:41], v[20:21], v[88:89]
	v_pk_fma_f32 v[30:31], v[34:35], v[30:31], v[82:83]
	v_pk_fma_f32 v[20:21], v[56:57], v[4:5], v[20:21]
	v_pk_fma_f32 v[30:31], v[50:51], v[14:15], v[30:31]
	v_pk_fma_f32 v[22:23], v[42:43], v[22:23], v[90:91]
	s_mov_b32 s39, 0x14200000
	v_pk_fma_f32 v[22:23], v[58:59], v[6:7], v[22:23]
	v_pk_fma_f32 v[8:9], v[36:37], v[8:9], v[84:85]
	v_pk_fma_f32 v[0:1], v[44:45], v[0:1], v[92:93]
	v_pk_fma_f32 v[10:11], v[38:39], v[10:11], v[86:87]
	v_pk_fma_f32 v[2:3], v[46:47], v[2:3], v[94:95]
	v_pk_fma_f32 v[12:13], v[32:33], v[12:13], v[80:81]
	v_pk_fma_f32 v[4:5], v[40:41], v[4:5], v[88:89]
	v_pk_fma_f32 v[14:15], v[34:35], v[14:15], v[82:83]
	v_pk_fma_f32 v[6:7], v[42:43], v[6:7], v[90:91]
	s_mov_b64 s[40:41], 0x5800
	s_add_i32 s38, s38, -4
	s_cmp_eq_u32 s38, 0
	s_waitcnt vmcnt(7)
	v_lshlrev_b32_e32 v106, 16, v144
	v_and_b32_e32 v107, 0xffff0000, v144
	v_pk_fma_f32 v[24:25], v[68:69], v[106:107], v[24:25]
	v_lshlrev_b32_e32 v108, 16, v145
	v_mul_f32_e32 v99, 0x3d372713, v24
	v_mul_f32_e32 v99, v24, v99
	v_fma_f32 v99, v24, v99, v24
	v_mul_f32_e32 v99, 0x3f4c422a, v99
	v_mul_f32_e32 v99, 0xc038aa3b, v99
	v_exp_f32_e32 v99, v99
	s_waitcnt vmcnt(6)
	v_lshlrev_b32_e32 v114, 16, v148
	v_and_b32_e32 v115, 0xffff0000, v148
	v_and_b32_e32 v109, 0xffff0000, v145
	v_add_f32_e32 v99, 1.0, v99
	v_rcp_f32_e32 v122, v99
	v_mul_f32_e32 v99, 0x3d372713, v25
	v_mul_f32_e32 v99, v25, v99
	v_fma_f32 v99, v25, v99, v25
	v_mul_f32_e32 v99, 0x3f4c422a, v99
	v_mul_f32_e32 v99, 0xc038aa3b, v99
	v_exp_f32_e32 v99, v99
	v_pk_fma_f32 v[16:17], v[76:77], v[114:115], v[16:17]
	v_pk_fma_f32 v[26:27], v[70:71], v[108:109], v[26:27]
	v_lshlrev_b32_e32 v116, 16, v149
	v_add_f32_e32 v99, 1.0, v99
	v_rcp_f32_e32 v123, v99
	v_and_b32_e32 v117, 0xffff0000, v149
	v_lshlrev_b32_e32 v110, 16, v146
	v_and_b32_e32 v111, 0xffff0000, v146
	v_pk_mul_f32 v[24:25], v[24:25], v[122:123]
	v_pk_fma_f32 v[18:19], v[78:79], v[116:117], v[18:19]
	v_pk_mul_f32 v[16:17], v[16:17], v[24:25]
	v_pk_fma_f32 v[28:29], v[64:65], v[110:111], v[28:29]
	v_cvt_pk_bf16_f32 v16, v16, v17
	v_mul_f32_e32 v17, 0x3d372713, v26
	v_mul_f32_e32 v17, v26, v17
	v_fma_f32 v17, v26, v17, v26
	v_mul_f32_e32 v17, 0x3f4c422a, v17
	v_mul_f32_e32 v17, 0xc038aa3b, v17
	v_exp_f32_e32 v17, v17
	v_lshlrev_b32_e32 v118, 16, v150
	v_and_b32_e32 v119, 0xffff0000, v150
	v_lshlrev_b32_e32 v112, 16, v147
	v_add_f32_e32 v17, 1.0, v17
	v_rcp_f32_e32 v24, v17
	v_mul_f32_e32 v17, 0x3d372713, v27
	v_mul_f32_e32 v17, v27, v17
	v_fma_f32 v17, v27, v17, v27
	v_mul_f32_e32 v17, 0x3f4c422a, v17
	v_mul_f32_e32 v17, 0xc038aa3b, v17
	v_exp_f32_e32 v17, v17
	v_and_b32_e32 v113, 0xffff0000, v147
	global_load_dwordx4 v[144:147], v[176:177], off nt
	v_pk_fma_f32 v[20:21], v[72:73], v[118:119], v[20:21]
	v_pk_fma_f32 v[30:31], v[66:67], v[112:113], v[30:31]
	v_add_f32_e32 v17, 1.0, v17
	v_rcp_f32_e32 v25, v17
	v_lshlrev_b32_e32 v120, 16, v151
	v_and_b32_e32 v121, 0xffff0000, v151
	v_lshl_add_u64 v[176:177], v[176:177], 0, s[46:47]
	global_load_dwordx4 v[148:151], v[176:177], off offset:-2560 nt
	v_pk_fma_f32 v[22:23], v[74:75], v[120:121], v[22:23]
	v_pk_mul_f32 v[24:25], v[26:27], v[24:25]
	v_lshl_add_u64 v[122:123], v[100:101], 0, v[96:97]
	v_pk_mul_f32 v[18:19], v[18:19], v[24:25]
	v_pk_fma_f32 v[8:9], v[52:53], v[106:107], v[8:9]
	v_cvt_pk_bf16_f32 v17, v18, v19
	v_mul_f32_e32 v18, 0x3d372713, v28
	v_mul_f32_e32 v19, 0x3d372713, v29
	v_mul_f32_e32 v18, v28, v18
	v_mul_f32_e32 v19, v29, v19
	v_fma_f32 v18, v28, v18, v28
	v_fma_f32 v19, v29, v19, v29
	v_mul_f32_e32 v18, 0x3f4c422a, v18
	v_mul_f32_e32 v19, 0x3f4c422a, v19
	v_mul_f32_e32 v18, 0xc038aa3b, v18
	v_mul_f32_e32 v19, 0xc038aa3b, v19
	v_exp_f32_e32 v18, v18
; DI unsigned pk2(float a, float b) { f32x2 v = {a, b}; bf16x2_t r = __builtin_convertvector(v, bf16x2_t); return __builtin_bit_cast(unsigned, r); }
; DI float gelu_tanh(float x) { const float u = 0.7978845608028654f * (x + 0.044715f * x * x * x); return x * __builtin_amdgcn_rcpf(1.f + __builtin_amdgcn_exp2f(-2.f * 1.4426950408889634f * u)); }
; DI f32x8_ unpk8(u32x4 a) { return (f32x8_){bflo(a.x), bfhi(a.x), bflo(a.y), bfhi(a.y), bflo(a.z), bfhi(a.z), bflo(a.w), bfhi(a.w)}; }
; DI void conv_phase(const bf16_t* UP, bf16_t* ACT, const float* cw, const float* cb, int gtid, int nthr) {
;     ...
;             const f32x8_ g0 = unpk8(__builtin_nontemporal_load((const u32x4*)(up + (size_t)i * NUP))), v0 = unpk8(__builtin_nontemporal_load((const u32x4*)(up + (size_t)i * NUP + DFF)));
;             const f32x8_ cg_ = bg + wg[0] * g2 + wg[1] * g1 + wg[2] * g0, cv = bv + wv[0] * v2 + wv[1] * v1 + wv[2] * v0;
;             u32x4 o; o.x = pk2(gelu_tanh(cg_[0]) * cv[0], gelu_tanh(cg_[1]) * cv[1]); o.y = pk2(gelu_tanh(cg_[2]) * cv[2], gelu_tanh(cg_[3]) * cv[3]);
;             o.z = pk2(gelu_tanh(cg_[4]) * cv[4], gelu_tanh(cg_[5]) * cv[5]); o.w = pk2(gelu_tanh(cg_[6]) * cv[6], gelu_tanh(cg_[7]) * cv[7]);
;             __builtin_nontemporal_store(o, (u32x4*)(ACT + (size_t)(r0 + i) * DFF + c0));
;             g2 = g1; g1 = g0; v2 = v1; v1 = v0;
	v_exp_f32_e32 v19, v19
	v_pk_fma_f32 v[0:1], v[60:61], v[114:115], v[0:1]
	v_pk_fma_f32 v[10:11], v[54:55], v[108:109], v[10:11]
	v_add_f32_e32 v18, 1.0, v18
	v_add_f32_e32 v19, 1.0, v19
	v_rcp_f32_e32 v18, v18
	v_rcp_f32_e32 v19, v19
	v_pk_fma_f32 v[2:3], v[62:63], v[116:117], v[2:3]
	v_pk_fma_f32 v[12:13], v[48:49], v[110:111], v[12:13]
	v_pk_fma_f32 v[4:5], v[56:57], v[118:119], v[4:5]
	v_pk_mul_f32 v[18:19], v[28:29], v[18:19]
	v_pk_fma_f32 v[14:15], v[50:51], v[112:113], v[14:15]
	v_pk_mul_f32 v[18:19], v[20:21], v[18:19]
	v_pk_fma_f32 v[6:7], v[58:59], v[120:121], v[6:7]
	v_cvt_pk_bf16_f32 v18, v18, v19
	v_mul_f32_e32 v19, 0x3d372713, v30
	v_mul_f32_e32 v19, v30, v19
	v_fma_f32 v19, v30, v19, v30
	v_mul_f32_e32 v19, 0x3f4c422a, v19
	v_mul_f32_e32 v19, 0xc038aa3b, v19
	v_exp_f32_e32 v19, v19
	v_lshl_add_u64 v[100:101], v[100:101], 0, s[40:41]
	s_mov_b64 s[40:41], 0xb000
	v_lshl_add_u64 v[102:103], v[102:103], 0, s[40:41]
	v_add_f32_e32 v19, 1.0, v19
	v_rcp_f32_e32 v20, v19
	v_mul_f32_e32 v19, 0x3d372713, v31
	v_mul_f32_e32 v19, v31, v19
	v_fma_f32 v19, v31, v19, v31
	v_mul_f32_e32 v19, 0x3f4c422a, v19
	v_mul_f32_e32 v19, 0xc038aa3b, v19
	v_exp_f32_e32 v19, v19
	s_nop 0
	v_add_f32_e32 v19, 1.0, v19
	v_rcp_f32_e32 v21, v19
	s_nop 0
	v_pk_mul_f32 v[20:21], v[30:31], v[20:21]
	s_nop 0
	v_pk_mul_f32 v[20:21], v[22:23], v[20:21]
	s_nop 0
	v_cvt_pk_bf16_f32 v19, v20, v21
	v_add_co_u32_e32 v20, vcc, s39, v122
	s_mov_b32 s39, 0x9202000
	s_nop 0
	v_addc_co_u32_e32 v21, vcc, 0, v123, vcc
	global_store_dwordx4 v[20:21], v[16:19], off nt
	s_nop 1
	s_mov_b32 s39, 0x9204000
	s_nop 0
	s_waitcnt vmcnt(8)
	v_lshlrev_b32_e32 v124, 16, v152
	v_and_b32_e32 v125, 0xffff0000, v152
	v_lshlrev_b32_e32 v126, 16, v153
	v_and_b32_e32 v127, 0xffff0000, v153
	v_lshlrev_b32_e32 v128, 16, v154
	v_and_b32_e32 v129, 0xffff0000, v154
	v_lshlrev_b32_e32 v130, 16, v155
	v_and_b32_e32 v131, 0xffff0000, v155
	global_load_dwordx4 v[152:155], v[176:177], off offset:3072 nt
	v_pk_fma_f32 v[8:9], v[68:69], v[124:125], v[8:9]
	v_pk_fma_f32 v[10:11], v[70:71], v[126:127], v[10:11]
	v_pk_fma_f32 v[12:13], v[64:65], v[128:129], v[12:13]
	v_pk_fma_f32 v[14:15], v[66:67], v[130:131], v[14:15]
	s_mov_b32 s39, 0x14201000
	s_waitcnt vmcnt(8)
	v_lshlrev_b32_e32 v132, 16, v156
	v_and_b32_e32 v133, 0xffff0000, v156
	v_lshlrev_b32_e32 v134, 16, v157
	v_and_b32_e32 v135, 0xffff0000, v157
	v_mul_f32_e32 v16, 0x3d372713, v8
	v_mul_f32_e32 v17, 0x3d372713, v9
	v_mul_f32_e32 v16, v8, v16
	v_mul_f32_e32 v17, v9, v17
	v_fma_f32 v16, v8, v16, v8
	v_fma_f32 v17, v9, v17, v9
	v_mul_f32_e32 v16, 0x3f4c422a, v16
	v_mul_f32_e32 v17, 0x3f4c422a, v17
	v_mul_f32_e32 v16, 0xc038aa3b, v16
	v_mul_f32_e32 v17, 0xc038aa3b, v17
	v_exp_f32_e32 v16, v16
	v_exp_f32_e32 v17, v17
	v_pk_fma_f32 v[0:1], v[76:77], v[132:133], v[0:1]
	v_pk_fma_f32 v[2:3], v[78:79], v[134:135], v[2:3]
	v_add_f32_e32 v16, 1.0, v16
	v_add_f32_e32 v17, 1.0, v17
	v_rcp_f32_e32 v16, v16
	v_rcp_f32_e32 v17, v17
	v_lshlrev_b32_e32 v136, 16, v158
	v_and_b32_e32 v137, 0xffff0000, v158
	v_pk_fma_f32 v[4:5], v[72:73], v[136:137], v[4:5]
	v_pk_mul_f32 v[8:9], v[8:9], v[16:17]
	v_lshlrev_b32_e32 v138, 16, v159
	v_pk_mul_f32 v[0:1], v[0:1], v[8:9]
	v_and_b32_e32 v139, 0xffff0000, v159
	v_lshl_add_u64 v[176:177], v[176:177], 0, s[46:47]
	global_load_dwordx4 v[156:159], v[176:177], off offset:512 nt
	v_cvt_pk_bf16_f32 v0, v0, v1
	v_mul_f32_e32 v1, 0x3d372713, v10
	v_mul_f32_e32 v1, v10, v1
	v_fma_f32 v1, v10, v1, v10
	v_mul_f32_e32 v1, 0x3f4c422a, v1
	v_mul_f32_e32 v1, 0xc038aa3b, v1
	v_exp_f32_e32 v1, v1
	v_pk_fma_f32 v[6:7], v[74:75], v[138:139], v[6:7]
	v_add_f32_e32 v1, 1.0, v1
	v_rcp_f32_e32 v8, v1
	v_mul_f32_e32 v1, 0x3d372713, v11
	v_mul_f32_e32 v1, v11, v1
	v_fma_f32 v1, v11, v1, v11
	v_mul_f32_e32 v1, 0x3f4c422a, v1
	v_mul_f32_e32 v1, 0xc038aa3b, v1
	v_exp_f32_e32 v1, v1
	s_nop 0
	v_add_f32_e32 v1, 1.0, v1
	v_rcp_f32_e32 v9, v1
	s_nop 0
	v_pk_mul_f32 v[8:9], v[10:11], v[8:9]
	s_nop 0
	v_pk_mul_f32 v[2:3], v[2:3], v[8:9]
	v_pk_fma_f32 v[10:11], v[40:41], v[118:119], v[88:89]
	v_cvt_pk_bf16_f32 v1, v2, v3
	v_mul_f32_e32 v2, 0x3d372713, v12
	v_mul_f32_e32 v3, 0x3d372713, v13
	v_mul_f32_e32 v2, v12, v2
	v_mul_f32_e32 v3, v13, v3
	v_fma_f32 v2, v12, v2, v12
	v_fma_f32 v3, v13, v3, v13
	v_mul_f32_e32 v2, 0x3f4c422a, v2
	v_mul_f32_e32 v3, 0x3f4c422a, v3
	v_mul_f32_e32 v2, 0xc038aa3b, v2
	v_mul_f32_e32 v3, 0xc038aa3b, v3
	v_exp_f32_e32 v2, v2
	v_exp_f32_e32 v3, v3
	v_pk_fma_f32 v[10:11], v[56:57], v[136:137], v[10:11]
	v_pk_fma_f32 v[118:119], v[44:45], v[132:133], v[92:93]
	v_add_f32_e32 v2, 1.0, v2
	v_add_f32_e32 v3, 1.0, v3
	v_rcp_f32_e32 v2, v2
	v_rcp_f32_e32 v3, v3
	s_nop 0
	v_pk_mul_f32 v[2:3], v[12:13], v[2:3]
	s_nop 0
	v_pk_mul_f32 v[2:3], v[4:5], v[2:3]
	v_pk_fma_f32 v[12:13], v[46:47], v[116:117], v[94:95]
	v_cvt_pk_bf16_f32 v2, v2, v3
	v_mul_f32_e32 v3, 0x3d372713, v14
	v_mul_f32_e32 v3, v14, v3
	v_fma_f32 v3, v14, v3, v14
	v_mul_f32_e32 v3, 0x3f4c422a, v3
	v_mul_f32_e32 v3, 0xc038aa3b, v3
	v_exp_f32_e32 v3, v3
	v_pk_fma_f32 v[12:13], v[62:63], v[134:135], v[12:13]
	v_pk_fma_f32 v[116:117], v[46:47], v[134:135], v[94:95]
	v_add_f32_e32 v3, 1.0, v3
	v_rcp_f32_e32 v4, v3
	v_mul_f32_e32 v3, 0x3d372713, v15
	v_mul_f32_e32 v3, v15, v3
	v_fma_f32 v3, v15, v3, v15
	v_mul_f32_e32 v3, 0x3f4c422a, v3
	v_mul_f32_e32 v3, 0xc038aa3b, v3
	v_exp_f32_e32 v3, v3
	s_nop 0
	v_add_f32_e32 v3, 1.0, v3
	v_rcp_f32_e32 v5, v3
	s_nop 0
	v_pk_mul_f32 v[4:5], v[14:15], v[4:5]
	s_nop 0
	v_pk_mul_f32 v[4:5], v[6:7], v[4:5]
	v_pk_fma_f32 v[6:7], v[36:37], v[106:107], v[84:85]
	v_cvt_pk_bf16_f32 v3, v4, v5
	v_add_co_u32_e32 v4, vcc, s39, v122
	s_mov_b32 s39, 0x9205000
	s_nop 0
	v_addc_co_u32_e32 v5, vcc, 0, v123, vcc
	global_store_dwordx4 v[4:5], v[0:3], off offset:1536 nt
	v_pk_fma_f32 v[6:7], v[52:53], v[124:125], v[6:7]
	v_pk_fma_f32 v[14:15], v[44:45], v[114:115], v[92:93]
	s_mov_b32 s39, 0x9206000
	s_nop 0
	v_pk_fma_f32 v[4:5], v[38:39], v[108:109], v[86:87]
	v_pk_fma_f32 v[14:15], v[60:61], v[132:133], v[14:15]
	v_pk_fma_f32 v[4:5], v[54:55], v[126:127], v[4:5]
	v_pk_fma_f32 v[108:109], v[38:39], v[126:127], v[86:87]
	v_pk_fma_f32 v[114:115], v[40:41], v[136:137], v[88:89]
	s_waitcnt vmcnt(9)
; DI unsigned pk2(float a, float b) { f32x2 v = {a, b}; bf16x2_t r = __builtin_convertvector(v, bf16x2_t); return __builtin_bit_cast(unsigned, r); }
; DI float gelu_tanh(float x) { const float u = 0.7978845608028654f * (x + 0.044715f * x * x * x); return x * __builtin_amdgcn_rcpf(1.f + __builtin_amdgcn_exp2f(-2.f * 1.4426950408889634f * u)); }
; DI f32x8_ unpk8(u32x4 a) { return (f32x8_){bflo(a.x), bfhi(a.x), bflo(a.y), bfhi(a.y), bflo(a.z), bfhi(a.z), bflo(a.w), bfhi(a.w)}; }
; DI void conv_phase(const bf16_t* UP, bf16_t* ACT, const float* cw, const float* cb, int gtid, int nthr) {
;     ...
;             const f32x8_ g0 = unpk8(__builtin_nontemporal_load((const u32x4*)(up + (size_t)i * NUP))), v0 = unpk8(__builtin_nontemporal_load((const u32x4*)(up + (size_t)i * NUP + DFF)));
;             const f32x8_ cg_ = bg + wg[0] * g2 + wg[1] * g1 + wg[2] * g0, cv = bv + wv[0] * v2 + wv[1] * v1 + wv[2] * v0;
;             u32x4 o; o.x = pk2(gelu_tanh(cg_[0]) * cv[0], gelu_tanh(cg_[1]) * cv[1]); o.y = pk2(gelu_tanh(cg_[2]) * cv[2], gelu_tanh(cg_[3]) * cv[3]);
;             o.z = pk2(gelu_tanh(cg_[4]) * cv[4], gelu_tanh(cg_[5]) * cv[5]); o.w = pk2(gelu_tanh(cg_[6]) * cv[6], gelu_tanh(cg_[7]) * cv[7]);
;             __builtin_nontemporal_store(o, (u32x4*)(ACT + (size_t)(r0 + i) * DFF + c0));
;             g2 = g1; g1 = g0; v2 = v1; v1 = v0;
	v_lshlrev_b32_e32 v24, 16, v160
	v_and_b32_e32 v25, 0xffff0000, v160
	v_lshlrev_b32_e32 v26, 16, v161
	v_and_b32_e32 v27, 0xffff0000, v161
	v_lshlrev_b32_e32 v28, 16, v162
	v_and_b32_e32 v29, 0xffff0000, v162
	v_lshlrev_b32_e32 v30, 16, v163
	v_and_b32_e32 v31, 0xffff0000, v163
	v_lshl_add_u64 v[176:177], v[176:177], 0, s[46:47]
	global_load_dwordx4 v[160:163], v[176:177], off offset:-2048 nt
	v_pk_fma_f32 v[4:5], v[70:71], v[26:27], v[4:5]
	s_mov_b32 s39, 0x14202000
	v_pk_fma_f32 v[108:109], v[54:55], v[26:27], v[108:109]
	s_waitcnt vmcnt(9)
	v_lshlrev_b32_e32 v16, 16, v164
	v_and_b32_e32 v17, 0xffff0000, v164
	v_lshlrev_b32_e32 v18, 16, v165
	v_and_b32_e32 v19, 0xffff0000, v165
	v_pk_fma_f32 v[0:1], v[34:35], v[112:113], v[82:83]
	v_pk_fma_f32 v[14:15], v[76:77], v[16:17], v[14:15]
	v_pk_fma_f32 v[0:1], v[50:51], v[130:131], v[0:1]
	v_lshlrev_b32_e32 v20, 16, v166
	v_pk_fma_f32 v[8:9], v[66:67], v[30:31], v[0:1]
	v_pk_fma_f32 v[0:1], v[68:69], v[24:25], v[6:7]
	v_and_b32_e32 v21, 0xffff0000, v166
	v_mul_f32_e32 v99, 0x3d372713, v0
	v_mul_f32_e32 v99, v0, v99
	v_fma_f32 v99, v0, v99, v0
	v_mul_f32_e32 v99, 0x3f4c422a, v99
	v_mul_f32_e32 v99, 0xc038aa3b, v99
	v_exp_f32_e32 v99, v99
	v_lshlrev_b32_e32 v22, 16, v167
	v_and_b32_e32 v23, 0xffff0000, v167
	global_load_dwordx4 v[164:167], v[176:177], off offset:3584 nt
	v_pk_fma_f32 v[2:3], v[32:33], v[110:111], v[80:81]
	v_add_f32_e32 v99, 1.0, v99
	v_rcp_f32_e32 v106, v99
	v_mul_f32_e32 v99, 0x3d372713, v1
	v_mul_f32_e32 v99, v1, v99
	v_fma_f32 v99, v1, v99, v1
	v_mul_f32_e32 v99, 0x3f4c422a, v99
	v_mul_f32_e32 v99, 0xc038aa3b, v99
	v_exp_f32_e32 v99, v99
	v_pk_fma_f32 v[2:3], v[48:49], v[128:129], v[2:3]
	v_pk_fma_f32 v[12:13], v[78:79], v[18:19], v[12:13]
	v_pk_fma_f32 v[2:3], v[64:65], v[28:29], v[2:3]
	v_add_f32_e32 v99, 1.0, v99
	v_rcp_f32_e32 v107, v99
	v_pk_fma_f32 v[10:11], v[72:73], v[20:21], v[10:11]
	v_pk_fma_f32 v[6:7], v[42:43], v[120:121], v[90:91]
	v_pk_fma_f32 v[110:111], v[36:37], v[124:125], v[84:85]
	v_pk_mul_f32 v[0:1], v[0:1], v[106:107]
	v_pk_fma_f32 v[6:7], v[58:59], v[138:139], v[6:7]
	v_pk_mul_f32 v[0:1], v[14:15], v[0:1]
	v_pk_fma_f32 v[6:7], v[74:75], v[22:23], v[6:7]
	v_cvt_pk_bf16_f32 v0, v0, v1
	v_mul_f32_e32 v1, 0x3d372713, v4
	v_mul_f32_e32 v1, v4, v1
	v_fma_f32 v1, v4, v1, v4
	v_mul_f32_e32 v1, 0x3f4c422a, v1
	v_mul_f32_e32 v1, 0xc038aa3b, v1
	v_exp_f32_e32 v1, v1
	v_pk_fma_f32 v[110:111], v[52:53], v[24:25], v[110:111]
	v_pk_fma_f32 v[118:119], v[60:61], v[16:17], v[118:119]
	v_pk_fma_f32 v[106:107], v[32:33], v[128:129], v[80:81]
	v_add_f32_e32 v1, 1.0, v1
	v_rcp_f32_e32 v14, v1
	v_mul_f32_e32 v1, 0x3d372713, v5
	v_mul_f32_e32 v1, v5, v1
	v_fma_f32 v1, v5, v1, v5
	v_mul_f32_e32 v1, 0x3f4c422a, v1
	v_mul_f32_e32 v1, 0xc038aa3b, v1
	v_exp_f32_e32 v1, v1
	v_pk_fma_f32 v[106:107], v[48:49], v[28:29], v[106:107]
	v_pk_fma_f32 v[116:117], v[62:63], v[18:19], v[116:117]
	v_pk_fma_f32 v[114:115], v[56:57], v[20:21], v[114:115]
	v_add_f32_e32 v1, 1.0, v1
	v_rcp_f32_e32 v15, v1
	s_nop 0
	v_pk_mul_f32 v[4:5], v[4:5], v[14:15]
	s_nop 0
	v_pk_mul_f32 v[4:5], v[12:13], v[4:5]
	s_nop 0
	v_cvt_pk_bf16_f32 v1, v4, v5
	v_mul_f32_e32 v4, 0x3d372713, v2
	v_mul_f32_e32 v5, 0x3d372713, v3
	v_mul_f32_e32 v4, v2, v4
	v_mul_f32_e32 v5, v3, v5
	v_fma_f32 v4, v2, v4, v2
	v_fma_f32 v5, v3, v5, v3
	v_mul_f32_e32 v4, 0x3f4c422a, v4
	v_mul_f32_e32 v5, 0x3f4c422a, v5
	v_mul_f32_e32 v4, 0xc038aa3b, v4
	v_mul_f32_e32 v5, 0xc038aa3b, v5
	v_exp_f32_e32 v4, v4
	v_exp_f32_e32 v5, v5
	v_add_f32_e32 v4, 1.0, v4
	v_add_f32_e32 v5, 1.0, v5
	v_rcp_f32_e32 v4, v4
	v_rcp_f32_e32 v5, v5
	s_nop 0
	v_pk_mul_f32 v[2:3], v[2:3], v[4:5]
	s_nop 0
	v_pk_mul_f32 v[2:3], v[10:11], v[2:3]
	s_nop 0
	v_cvt_pk_bf16_f32 v2, v2, v3
	v_mul_f32_e32 v3, 0x3d372713, v8
	v_mul_f32_e32 v3, v8, v3
	v_fma_f32 v3, v8, v3, v8
	v_mul_f32_e32 v3, 0x3f4c422a, v3
	v_mul_f32_e32 v3, 0xc038aa3b, v3
	v_exp_f32_e32 v3, v3
	s_nop 0
	v_add_f32_e32 v3, 1.0, v3
	v_rcp_f32_e32 v4, v3
	v_mul_f32_e32 v3, 0x3d372713, v9
	v_mul_f32_e32 v3, v9, v3
	v_fma_f32 v3, v9, v3, v9
	v_mul_f32_e32 v3, 0x3f4c422a, v3
	v_mul_f32_e32 v3, 0xc038aa3b, v3
	v_exp_f32_e32 v3, v3
	s_nop 0
	v_add_f32_e32 v3, 1.0, v3
	v_rcp_f32_e32 v5, v3
	s_nop 0
	v_pk_mul_f32 v[4:5], v[8:9], v[4:5]
	s_nop 0
	v_pk_mul_f32 v[4:5], v[6:7], v[4:5]
	s_nop 0
	v_cvt_pk_bf16_f32 v3, v4, v5
	v_add_co_u32_e32 v4, vcc, s39, v122
	s_mov_b32 s39, 0x9208000
	s_nop 0
	v_addc_co_u32_e32 v5, vcc, 0, v123, vcc
	global_store_dwordx4 v[4:5], v[0:3], off offset:3072 nt
	s_nop 1
	s_mov_b32 s39, 0x9209000
	s_nop 0
	s_waitcnt vmcnt(10)
; DI unsigned pk2(float a, float b) { f32x2 v = {a, b}; bf16x2_t r = __builtin_convertvector(v, bf16x2_t); return __builtin_bit_cast(unsigned, r); }
; DI float gelu_tanh(float x) { const float u = 0.7978845608028654f * (x + 0.044715f * x * x * x); return x * __builtin_amdgcn_rcpf(1.f + __builtin_amdgcn_exp2f(-2.f * 1.4426950408889634f * u)); }
; DI f32x8_ unpk8(u32x4 a) { return (f32x8_){bflo(a.x), bfhi(a.x), bflo(a.y), bfhi(a.y), bflo(a.z), bfhi(a.z), bflo(a.w), bfhi(a.w)}; }
; DI void conv_phase(const bf16_t* UP, bf16_t* ACT, const float* cw, const float* cb, int gtid, int nthr) {
;     ...
;             const f32x8_ g0 = unpk8(__builtin_nontemporal_load((const u32x4*)(up + (size_t)i * NUP))), v0 = unpk8(__builtin_nontemporal_load((const u32x4*)(up + (size_t)i * NUP + DFF)));
;             const f32x8_ cg_ = bg + wg[0] * g2 + wg[1] * g1 + wg[2] * g0, cv = bv + wv[0] * v2 + wv[1] * v1 + wv[2] * v0;
;             u32x4 o; o.x = pk2(gelu_tanh(cg_[0]) * cv[0], gelu_tanh(cg_[1]) * cv[1]); o.y = pk2(gelu_tanh(cg_[2]) * cv[2], gelu_tanh(cg_[3]) * cv[3]);
;             o.z = pk2(gelu_tanh(cg_[4]) * cv[4], gelu_tanh(cg_[5]) * cv[5]); o.w = pk2(gelu_tanh(cg_[6]) * cv[6], gelu_tanh(cg_[7]) * cv[7]);
;             __builtin_nontemporal_store(o, (u32x4*)(ACT + (size_t)(r0 + i) * DFF + c0));
;             g2 = g1; g1 = g0; v2 = v1; v1 = v0;
;         }
;     }
; }
	v_lshlrev_b32_e32 v8, 16, v168
	v_and_b32_e32 v9, 0xffff0000, v168
	v_lshlrev_b32_e32 v10, 16, v169
	v_and_b32_e32 v11, 0xffff0000, v169
	v_pk_fma_f32 v[104:105], v[34:35], v[130:131], v[82:83]
	v_lshlrev_b32_e32 v14, 16, v171
	v_and_b32_e32 v15, 0xffff0000, v171
	v_pk_fma_f32 v[104:105], v[50:51], v[30:31], v[104:105]
	v_pk_fma_f32 v[108:109], v[70:71], v[10:11], v[108:109]
	v_pk_fma_f32 v[112:113], v[66:67], v[14:15], v[104:105]
	v_pk_fma_f32 v[104:105], v[68:69], v[8:9], v[110:111]
	v_lshlrev_b32_e32 v12, 16, v170
	v_mul_f32_e32 v99, 0x3d372713, v104
	v_mul_f32_e32 v99, v104, v99
	v_fma_f32 v99, v104, v99, v104
	v_mul_f32_e32 v99, 0x3f4c422a, v99
	v_mul_f32_e32 v99, 0xc038aa3b, v99
	v_exp_f32_e32 v99, v99
	v_and_b32_e32 v13, 0xffff0000, v170
	v_lshl_add_u64 v[176:177], v[176:177], 0, s[46:47]
	global_load_dwordx4 v[168:171], v[176:177], off offset:1024 nt
	v_pk_fma_f32 v[106:107], v[64:65], v[12:13], v[106:107]
	v_pk_fma_f32 v[110:111], v[42:43], v[138:139], v[90:91]
	v_add_f32_e32 v99, 1.0, v99
	v_rcp_f32_e32 v120, v99
	v_mul_f32_e32 v99, 0x3d372713, v105
	v_mul_f32_e32 v99, v105, v99
	v_fma_f32 v99, v105, v99, v105
	v_mul_f32_e32 v99, 0x3f4c422a, v99
	v_mul_f32_e32 v99, 0xc038aa3b, v99
	v_exp_f32_e32 v99, v99
	v_pk_fma_f32 v[110:111], v[58:59], v[22:23], v[110:111]
	v_add_f32_e32 v99, 1.0, v99
	v_rcp_f32_e32 v121, v99
	v_mul_f32_e32 v99, 0x3d372713, v108
	v_mul_f32_e32 v99, v108, v99
	v_fma_f32 v99, v108, v99, v108
	v_mul_f32_e32 v99, 0x3f4c422a, v99
	v_mul_f32_e32 v99, 0xc038aa3b, v99
	v_exp_f32_e32 v99, v99
	v_pk_mul_f32 v[104:105], v[104:105], v[120:121]
	v_add_f32_e32 v99, 1.0, v99
	s_waitcnt vmcnt(10)
	v_lshlrev_b32_e32 v0, 16, v172
	v_and_b32_e32 v1, 0xffff0000, v172
	v_pk_fma_f32 v[118:119], v[76:77], v[0:1], v[118:119]
	v_lshlrev_b32_e32 v2, 16, v173
	v_pk_mul_f32 v[104:105], v[118:119], v[104:105]
	v_rcp_f32_e32 v118, v99
	v_mul_f32_e32 v99, 0x3d372713, v109
	v_mul_f32_e32 v99, v109, v99
	v_fma_f32 v99, v109, v99, v109
	v_mul_f32_e32 v99, 0x3f4c422a, v99
	v_mul_f32_e32 v99, 0xc038aa3b, v99
	v_exp_f32_e32 v99, v99
	v_and_b32_e32 v3, 0xffff0000, v173
	v_pk_fma_f32 v[116:117], v[78:79], v[2:3], v[116:117]
	v_cvt_pk_bf16_f32 v104, v104, v105
	v_add_f32_e32 v99, 1.0, v99
	v_rcp_f32_e32 v119, v99
	v_mul_f32_e32 v99, 0x3d372713, v106
	v_mul_f32_e32 v99, v106, v99
	v_fma_f32 v99, v106, v99, v106
	v_mul_f32_e32 v99, 0x3f4c422a, v99
	v_mul_f32_e32 v99, 0xc038aa3b, v99
	v_exp_f32_e32 v99, v99
	v_pk_mul_f32 v[108:109], v[108:109], v[118:119]
	v_lshlrev_b32_e32 v4, 16, v174
	v_pk_mul_f32 v[108:109], v[116:117], v[108:109]
	v_add_f32_e32 v99, 1.0, v99
	v_cvt_pk_bf16_f32 v105, v108, v109
	v_rcp_f32_e32 v108, v99
	v_mul_f32_e32 v99, 0x3d372713, v107
	v_mul_f32_e32 v99, v107, v99
	v_fma_f32 v99, v107, v99, v107
	v_mul_f32_e32 v99, 0x3f4c422a, v99
	v_mul_f32_e32 v99, 0xc038aa3b, v99
	v_exp_f32_e32 v99, v99
	v_and_b32_e32 v5, 0xffff0000, v174
	v_lshlrev_b32_e32 v6, 16, v175
	v_and_b32_e32 v7, 0xffff0000, v175
	v_lshl_add_u64 v[176:177], v[176:177], 0, s[46:47]
	global_load_dwordx4 v[172:175], v[176:177], off offset:-1536 nt
	v_add_f32_e32 v99, 1.0, v99
	v_rcp_f32_e32 v109, v99
	v_mul_f32_e32 v99, 0x3d372713, v112
	v_mul_f32_e32 v99, v112, v99
	v_fma_f32 v99, v112, v99, v112
	v_mul_f32_e32 v99, 0x3f4c422a, v99
	v_mul_f32_e32 v99, 0xc038aa3b, v99
	v_exp_f32_e32 v99, v99
	v_pk_mul_f32 v[106:107], v[106:107], v[108:109]
	v_pk_fma_f32 v[110:111], v[74:75], v[6:7], v[110:111]
	v_pk_fma_f32 v[114:115], v[72:73], v[4:5], v[114:115]
	v_add_f32_e32 v99, 1.0, v99
	v_rcp_f32_e32 v108, v99
	v_mul_f32_e32 v99, 0x3d372713, v113
	v_mul_f32_e32 v99, v113, v99
	v_fma_f32 v99, v113, v99, v113
	v_mul_f32_e32 v99, 0x3f4c422a, v99
	v_mul_f32_e32 v99, 0xc038aa3b, v99
	v_exp_f32_e32 v99, v99
	v_pk_mul_f32 v[106:107], v[114:115], v[106:107]
	v_add_f32_e32 v99, 1.0, v99
	v_rcp_f32_e32 v109, v99
	v_cvt_pk_bf16_f32 v106, v106, v107
	v_pk_mul_f32 v[108:109], v[112:113], v[108:109]
	s_nop 0
	v_pk_mul_f32 v[108:109], v[110:111], v[108:109]
	s_nop 0
	v_cvt_pk_bf16_f32 v107, v108, v109
	v_add_co_u32_e32 v108, vcc, 0x14204000, v122
	s_nop 1
	v_addc_co_u32_e32 v109, vcc, 0, v123, vcc
	global_store_dwordx4 v[108:109], v[104:107], off offset:512 nt
	s_cbranch_scc0 .LBB0_913
	v_add_u32_e32 v140, s88, v140
	s_mov_b32 s38, 0x57fff
	v_cmp_lt_i32_e32 vcc, s38, v140
	s_or_b64 s[36:37], vcc, s[36:37]
	s_andn2_b64 exec, exec, s[36:37]
	s_cbranch_execnz .LBB0_910
